# all s_setprio removed, no static raise
# speedup vs baseline: 1.0047x; 1.0047x over previous
_Z11mega_kernel6Params:
	v_readfirstlane_b32 s94, v0
	s_nop 3
	s_and_b32 s94, s94, 0x3ff
	s_lshr_b32 s94, s94, 6
	s_cmp_ge_u32 s94, 4
	s_cbranch_scc0 .Lprio_done
